# v13 + P1 gates epilogue: gate_bias vectors loaded once per unit instead of per block (no per-block vmcnt(0) drains)
# baseline (speedup 1.0000x reference)
; __device__ __forceinline__ float sigmoidf_(float x) { return __builtin_amdgcn_rcpf(1.0f + __expf(-x)); }
; __device__ __forceinline__ u32x4 pack8(const f32x4 v0, const f32x4 v1) { u32x4 w; w.x = cvt_pk_bf16(v0[0], v0[1]); w.y = cvt_pk_bf16(v0[2], v0[3]); w.z = cvt_pk_bf16(v1[0], v1[1]); w.w = cvt_pk_bf16(v1[2], v1[3]); return w; }
;     __device__ __forceinline__ void operator()(const Acc& acc, const Unit& u, int wr, int wc, int fr, int fq) const {
;     ...
;         } else {
;             const int colt = (pn - 55) * BM;
; #pragma unroll
;             for (int ai = 0; ai < 2; ++ai)
; #pragma unroll
;                 for (int m = 0; m < 4; ++m) { const int row = row0 + ai * HALF + m * 16;
; #pragma unroll
;                     for (int bj = 0; bj < 2; ++bj) { const int col = colt + bj * HALF + cw; const f32x4 b0 = *(const f32x4*)(gbias + col), b1 = *(const f32x4*)(gbias + col + 4); f32x4 v[2];
; #pragma unroll
;                         for (int j = 0; j < 4; ++j) { v[0][j] = sigmoidf_(acc[ai][bj][m][0][j] + b0[j]); v[1][j] = sigmoidf_(acc[ai][bj][m][1][j] + b1[j]); }
;                         *(u32x4*)(GT + (size_t)row * GTP + col) = pack8(v[0], v[1]); } }
.LBB0_228:
	v_mbcnt_lo_u32_b32 v157, -1, 0
	v_mbcnt_hi_u32_b32 v157, -1, v157
	s_lshl_b32 s0, s54, 8
	v_ashrrev_i32_e32 v132, 4, v157
	v_and_b32_e32 v139, 15, v157
	s_add_i32 s1, s0, s90
	v_lshlrev_b32_e32 v142, 3, v132
	v_mov_b32_e32 v128, v132
	v_or_b32_e32 v138, s1, v139
	v_add_u32_e32 v140, s93, v142
	s_cmp_gt_i32 s46, 5
	s_mov_b64 s[58:59], -1
	s_cbranch_scc0 .LBB0_246
	v_lshlrev_b32_e32 v143, 3, v128
	s_cmp_lg_u32 s46, 6
	s_cbranch_scc0 .LBB0_243
	s_cmp_gt_u32 s46, 22
	s_cbranch_scc0 .LBB0_240
	s_cmp_gt_u32 s46, 38
	s_cbranch_scc0 .LBB0_237
	s_lshl_b32 s1, s46, 8
	s_cmp_gt_u32 s46, 54
	s_cbranch_scc0 .LBB0_234
	s_add_i32 s6, s1, 0xffffc900
	v_add_u32_e32 v148, s6, v140
	s_mov_b32 s6, s20
	s_mov_b32 s39, s21
	v_readlane_b32 s16, v237, 3
	v_ashrrev_i32_e32 v149, 31, v148
	v_readlane_b32 s24, v237, 11
	v_readlane_b32 s25, v237, 12
	v_readlane_b32 s20, v237, 7
	v_readlane_b32 s22, v237, 9
	v_lshl_add_u64 v[144:145], v[148:149], 2, s[24:25]
	global_load_dwordx4 v[128:131], v[144:145], off offset:16
	global_load_dwordx4 v[158:161], v[144:145], off
	global_load_dwordx4 v[176:179], v[144:145], off offset:16
	global_load_dwordx4 v[180:183], v[144:145], off
	global_load_dwordx4 v[184:187], v[144:145], off offset:528
	global_load_dwordx4 v[188:191], v[144:145], off offset:512
	v_readlane_b32 s23, v237, 10
	s_mov_b32 s20, s6
	s_movk_i32 s6, 0x4100
	v_lshlrev_b64 v[148:149], 1, v[148:149]
	v_readlane_b32 s21, v237, 8
	v_readlane_b32 s17, v237, 4
	v_readlane_b32 s18, v237, 5
	v_readlane_b32 s19, v237, 6
	v_readlane_b32 s26, v237, 13
	v_readlane_b32 s27, v237, 14
	v_readlane_b32 s28, v237, 15
	v_readlane_b32 s29, v237, 16
	v_readlane_b32 s30, v237, 17
	v_readlane_b32 s31, v237, 18
	s_mov_b32 s21, s39
	s_mov_b64 s[58:59], 0
	s_waitcnt vmcnt(0)
	v_add_f32_e32 v129, v121, v129
	v_add_f32_e32 v130, v122, v130
	v_mul_f32_e32 v129, 0xbfb8aa3b, v129
	v_mul_f32_e32 v130, 0xbfb8aa3b, v130
	v_add_f32_e32 v128, v120, v128
	v_exp_f32_e32 v129, v129
	v_exp_f32_e32 v130, v130
	v_mul_f32_e32 v128, 0xbfb8aa3b, v128
	v_exp_f32_e32 v128, v128
	v_add_f32_e32 v129, 1.0, v129
	v_add_f32_e32 v130, 1.0, v130
	v_rcp_f32_e32 v147, v129
	v_add_f32_e32 v129, v126, v160
	v_rcp_f32_e32 v150, v130
	v_add_f32_e32 v130, v127, v161
	v_add_f32_e32 v128, 1.0, v128
	v_mul_f32_e32 v129, 0xbfb8aa3b, v129
	v_mul_f32_e32 v130, 0xbfb8aa3b, v130
	v_add_f32_e32 v131, v123, v131
	v_add_f32_e32 v141, v124, v158
	v_rcp_f32_e32 v146, v128
	v_add_f32_e32 v128, v125, v159
	v_exp_f32_e32 v129, v129
	v_exp_f32_e32 v130, v130
	v_mul_f32_e32 v131, 0xbfb8aa3b, v131
	v_mul_f32_e32 v141, 0xbfb8aa3b, v141
	v_mul_f32_e32 v128, 0xbfb8aa3b, v128
	v_exp_f32_e32 v131, v131
	v_exp_f32_e32 v141, v141
	v_exp_f32_e32 v128, v128
	v_add_f32_e32 v129, 1.0, v129
	v_add_f32_e32 v130, 1.0, v130
	v_rcp_f32_e32 v129, v129
	v_rcp_f32_e32 v130, v130
	v_add_f32_e32 v131, 1.0, v131
	v_add_f32_e32 v141, 1.0, v141
	v_add_f32_e32 v128, 1.0, v128
	v_rcp_f32_e32 v131, v131
	v_rcp_f32_e32 v141, v141
	v_rcp_f32_e32 v128, v128
	v_cvt_pk_bf16_f32 v129, v129, v130
	v_cvt_pk_bf16_f32 v130, v146, v147
	v_mov_b64_e32 v[146:147], s[80:81]
	v_cvt_pk_bf16_f32 v131, v150, v131
	v_mad_i64_i32 v[150:151], s[22:23], v138, s6, v[146:147]
	v_cvt_pk_bf16_f32 v128, v141, v128
	v_lshl_add_u64 v[150:151], v[150:151], 0, v[148:149]
	global_store_dwordx4 v[150:151], v[128:131], off
	s_nop 1
	v_add_f32_e32 v128, v112, v184
	v_add_f32_e32 v129, v113, v185
	v_add_f32_e32 v130, v114, v186
	v_mul_f32_e32 v128, 0xbfb8aa3b, v128
	v_mul_f32_e32 v129, 0xbfb8aa3b, v129
	v_mul_f32_e32 v130, 0xbfb8aa3b, v130
	v_exp_f32_e32 v128, v128
	v_exp_f32_e32 v129, v129
	v_exp_f32_e32 v130, v130
	v_add_f32_e32 v141, v116, v188
	v_add_f32_e32 v128, 1.0, v128
	v_add_f32_e32 v129, 1.0, v129
	v_add_f32_e32 v130, 1.0, v130
	v_rcp_f32_e32 v158, v128
	v_add_f32_e32 v128, v117, v189
	v_rcp_f32_e32 v159, v129
	v_add_f32_e32 v129, v118, v190
	v_rcp_f32_e32 v160, v130
	v_add_f32_e32 v130, v119, v191
	v_add_f32_e32 v131, v115, v187
	v_mul_f32_e32 v141, 0xbfb8aa3b, v141
	v_mul_f32_e32 v128, 0xbfb8aa3b, v128
	v_mul_f32_e32 v129, 0xbfb8aa3b, v129
	v_mul_f32_e32 v130, 0xbfb8aa3b, v130
	v_mul_f32_e32 v131, 0xbfb8aa3b, v131
	v_exp_f32_e32 v141, v141
	v_exp_f32_e32 v128, v128
	v_exp_f32_e32 v129, v129
	v_exp_f32_e32 v130, v130
	v_exp_f32_e32 v131, v131
	v_add_f32_e32 v141, 1.0, v141
	v_add_f32_e32 v128, 1.0, v128
	v_add_f32_e32 v129, 1.0, v129
	v_add_f32_e32 v130, 1.0, v130
	v_add_f32_e32 v131, 1.0, v131
	v_rcp_f32_e32 v141, v141
	v_rcp_f32_e32 v128, v128
	v_rcp_f32_e32 v129, v129
	v_rcp_f32_e32 v130, v130
	v_rcp_f32_e32 v131, v131
	v_cvt_pk_bf16_f32 v128, v141, v128
	v_or_b32_e32 v141, 16, v138
	v_cvt_pk_bf16_f32 v129, v129, v130
	v_cvt_pk_bf16_f32 v130, v158, v159
	v_cvt_pk_bf16_f32 v131, v160, v131
	global_store_dwordx4 v[150:151], v[128:131], off offset:256
	s_nop 1
	v_add_f32_e32 v128, v104, v176
	v_add_f32_e32 v129, v105, v177
	v_add_f32_e32 v130, v106, v178
	v_mul_f32_e32 v128, 0xbfb8aa3b, v128
	v_mul_f32_e32 v129, 0xbfb8aa3b, v129
	v_mul_f32_e32 v130, 0xbfb8aa3b, v130
	v_exp_f32_e32 v128, v128
	v_exp_f32_e32 v129, v129
	v_exp_f32_e32 v130, v130
	v_add_f32_e32 v150, v108, v180
	v_add_f32_e32 v128, 1.0, v128
	v_add_f32_e32 v129, 1.0, v129
	v_add_f32_e32 v130, 1.0, v130
	v_rcp_f32_e32 v151, v128
	v_add_f32_e32 v128, v109, v181
	v_rcp_f32_e32 v158, v129
	v_add_f32_e32 v129, v110, v182
	v_rcp_f32_e32 v159, v130
	v_add_f32_e32 v130, v111, v183
	v_mul_f32_e32 v150, 0xbfb8aa3b, v150
	v_mul_f32_e32 v128, 0xbfb8aa3b, v128
	v_mul_f32_e32 v129, 0xbfb8aa3b, v129
	v_mul_f32_e32 v130, 0xbfb8aa3b, v130
	v_add_f32_e32 v131, v107, v179
	v_exp_f32_e32 v150, v150
	v_exp_f32_e32 v128, v128
; __device__ __forceinline__ float sigmoidf_(float x) { return __builtin_amdgcn_rcpf(1.0f + __expf(-x)); }
; __device__ __forceinline__ u32x4 pack8(const f32x4 v0, const f32x4 v1) { u32x4 w; w.x = cvt_pk_bf16(v0[0], v0[1]); w.y = cvt_pk_bf16(v0[2], v0[3]); w.z = cvt_pk_bf16(v1[0], v1[1]); w.w = cvt_pk_bf16(v1[2], v1[3]); return w; }
;     __device__ __forceinline__ void operator()(const Acc& acc, const Unit& u, int wr, int wc, int fr, int fq) const {
;     ...
;             for (int ai = 0; ai < 2; ++ai)
; #pragma unroll
;                 for (int m = 0; m < 4; ++m) { const int row = row0 + ai * HALF + m * 16;
; #pragma unroll
;                     for (int bj = 0; bj < 2; ++bj) { const int col = colt + bj * HALF + cw; const f32x4 b0 = *(const f32x4*)(gbias + col), b1 = *(const f32x4*)(gbias + col + 4); f32x4 v[2];
; #pragma unroll
;                         for (int j = 0; j < 4; ++j) { v[0][j] = sigmoidf_(acc[ai][bj][m][0][j] + b0[j]); v[1][j] = sigmoidf_(acc[ai][bj][m][1][j] + b1[j]); }
;                         *(u32x4*)(GT + (size_t)row * GTP + col) = pack8(v[0], v[1]); } }
	v_exp_f32_e32 v129, v129
	v_exp_f32_e32 v130, v130
	v_mul_f32_e32 v131, 0xbfb8aa3b, v131
	v_exp_f32_e32 v131, v131
	v_add_f32_e32 v150, 1.0, v150
	v_add_f32_e32 v128, 1.0, v128
	v_add_f32_e32 v129, 1.0, v129
	v_add_f32_e32 v130, 1.0, v130
	v_rcp_f32_e32 v150, v150
	v_rcp_f32_e32 v128, v128
	v_rcp_f32_e32 v129, v129
	v_rcp_f32_e32 v130, v130
	v_add_f32_e32 v131, 1.0, v131
	v_rcp_f32_e32 v131, v131
	v_cvt_pk_bf16_f32 v128, v150, v128
	v_cvt_pk_bf16_f32 v129, v129, v130
	v_cvt_pk_bf16_f32 v130, v151, v158
	v_mad_i64_i32 v[150:151], s[22:23], v141, s6, v[146:147]
	v_cvt_pk_bf16_f32 v131, v159, v131
	v_lshl_add_u64 v[150:151], v[150:151], 0, v[148:149]
	global_store_dwordx4 v[150:151], v[128:131], off
	s_nop 1
	v_add_f32_e32 v128, v96, v184
	v_add_f32_e32 v129, v97, v185
	v_add_f32_e32 v130, v98, v186
	v_mul_f32_e32 v128, 0xbfb8aa3b, v128
	v_mul_f32_e32 v129, 0xbfb8aa3b, v129
	v_mul_f32_e32 v130, 0xbfb8aa3b, v130
	v_exp_f32_e32 v128, v128
	v_exp_f32_e32 v129, v129
	v_exp_f32_e32 v130, v130
	v_add_f32_e32 v141, v100, v188
	v_add_f32_e32 v128, 1.0, v128
	v_add_f32_e32 v129, 1.0, v129
	v_add_f32_e32 v130, 1.0, v130
	v_rcp_f32_e32 v158, v128
	v_add_f32_e32 v128, v101, v189
	v_rcp_f32_e32 v159, v129
	v_add_f32_e32 v129, v102, v190
	v_rcp_f32_e32 v160, v130
	v_add_f32_e32 v130, v103, v191
	v_add_f32_e32 v131, v99, v187
	v_mul_f32_e32 v141, 0xbfb8aa3b, v141
	v_mul_f32_e32 v128, 0xbfb8aa3b, v128
	v_mul_f32_e32 v129, 0xbfb8aa3b, v129
	v_mul_f32_e32 v130, 0xbfb8aa3b, v130
	v_mul_f32_e32 v131, 0xbfb8aa3b, v131
	v_exp_f32_e32 v141, v141
	v_exp_f32_e32 v128, v128
	v_exp_f32_e32 v129, v129
	v_exp_f32_e32 v130, v130
	v_exp_f32_e32 v131, v131
	v_add_f32_e32 v141, 1.0, v141
	v_add_f32_e32 v128, 1.0, v128
	v_add_f32_e32 v129, 1.0, v129
	v_add_f32_e32 v130, 1.0, v130
	v_add_f32_e32 v131, 1.0, v131
	v_rcp_f32_e32 v141, v141
	v_rcp_f32_e32 v128, v128
	v_rcp_f32_e32 v129, v129
	v_rcp_f32_e32 v130, v130
	v_rcp_f32_e32 v131, v131
	v_cvt_pk_bf16_f32 v128, v141, v128
	v_or_b32_e32 v141, 32, v138
	v_cvt_pk_bf16_f32 v129, v129, v130
	v_cvt_pk_bf16_f32 v130, v158, v159
	v_cvt_pk_bf16_f32 v131, v160, v131
	global_store_dwordx4 v[150:151], v[128:131], off offset:256
	s_nop 1
	v_add_f32_e32 v128, v88, v176
	v_add_f32_e32 v129, v89, v177
	v_add_f32_e32 v130, v90, v178
	v_mul_f32_e32 v128, 0xbfb8aa3b, v128
	v_mul_f32_e32 v129, 0xbfb8aa3b, v129
	v_mul_f32_e32 v130, 0xbfb8aa3b, v130
	v_exp_f32_e32 v128, v128
	v_exp_f32_e32 v129, v129
	v_exp_f32_e32 v130, v130
	v_add_f32_e32 v150, v92, v180
	v_add_f32_e32 v128, 1.0, v128
	v_add_f32_e32 v129, 1.0, v129
	v_add_f32_e32 v130, 1.0, v130
	v_rcp_f32_e32 v151, v128
	v_add_f32_e32 v128, v93, v181
	v_rcp_f32_e32 v158, v129
	v_add_f32_e32 v129, v94, v182
	v_rcp_f32_e32 v159, v130
	v_add_f32_e32 v130, v95, v183
	v_mul_f32_e32 v150, 0xbfb8aa3b, v150
	v_mul_f32_e32 v128, 0xbfb8aa3b, v128
	v_mul_f32_e32 v129, 0xbfb8aa3b, v129
	v_mul_f32_e32 v130, 0xbfb8aa3b, v130
	v_add_f32_e32 v131, v91, v179
	v_exp_f32_e32 v150, v150
	v_exp_f32_e32 v128, v128
	v_exp_f32_e32 v129, v129
	v_exp_f32_e32 v130, v130
	v_mul_f32_e32 v131, 0xbfb8aa3b, v131
	v_exp_f32_e32 v131, v131
	v_add_f32_e32 v150, 1.0, v150
	v_add_f32_e32 v128, 1.0, v128
	v_add_f32_e32 v129, 1.0, v129
	v_add_f32_e32 v130, 1.0, v130
	v_rcp_f32_e32 v150, v150
	v_rcp_f32_e32 v128, v128
	v_rcp_f32_e32 v129, v129
	v_rcp_f32_e32 v130, v130
	v_add_f32_e32 v131, 1.0, v131
	v_rcp_f32_e32 v131, v131
	v_cvt_pk_bf16_f32 v128, v150, v128
	v_cvt_pk_bf16_f32 v129, v129, v130
	v_cvt_pk_bf16_f32 v130, v151, v158
	v_mad_i64_i32 v[150:151], s[22:23], v141, s6, v[146:147]
	v_cvt_pk_bf16_f32 v131, v159, v131
	v_lshl_add_u64 v[150:151], v[150:151], 0, v[148:149]
	global_store_dwordx4 v[150:151], v[128:131], off
	s_nop 1
	v_add_f32_e32 v128, v80, v184
	v_add_f32_e32 v129, v81, v185
	v_add_f32_e32 v130, v82, v186
	v_mul_f32_e32 v128, 0xbfb8aa3b, v128
	v_mul_f32_e32 v129, 0xbfb8aa3b, v129
	v_mul_f32_e32 v130, 0xbfb8aa3b, v130
	v_exp_f32_e32 v128, v128
	v_exp_f32_e32 v129, v129
	v_exp_f32_e32 v130, v130
	v_add_f32_e32 v141, v84, v188
	v_add_f32_e32 v128, 1.0, v128
	v_add_f32_e32 v129, 1.0, v129
	v_add_f32_e32 v130, 1.0, v130
	v_rcp_f32_e32 v158, v128
	v_add_f32_e32 v128, v85, v189
	v_rcp_f32_e32 v159, v129
	v_add_f32_e32 v129, v86, v190
	v_rcp_f32_e32 v160, v130
	v_add_f32_e32 v130, v87, v191
	v_add_f32_e32 v131, v83, v187
	v_mul_f32_e32 v141, 0xbfb8aa3b, v141
	v_mul_f32_e32 v128, 0xbfb8aa3b, v128
	v_mul_f32_e32 v129, 0xbfb8aa3b, v129
	v_mul_f32_e32 v130, 0xbfb8aa3b, v130
	v_mul_f32_e32 v131, 0xbfb8aa3b, v131
	v_exp_f32_e32 v141, v141
	v_exp_f32_e32 v128, v128
	v_exp_f32_e32 v129, v129
	v_exp_f32_e32 v130, v130
	v_exp_f32_e32 v131, v131
	v_add_f32_e32 v141, 1.0, v141
	v_add_f32_e32 v128, 1.0, v128
	v_add_f32_e32 v129, 1.0, v129
	v_add_f32_e32 v130, 1.0, v130
	v_add_f32_e32 v131, 1.0, v131
	v_rcp_f32_e32 v141, v141
	v_rcp_f32_e32 v128, v128
	v_rcp_f32_e32 v129, v129
	v_rcp_f32_e32 v130, v130
	v_rcp_f32_e32 v131, v131
	v_cvt_pk_bf16_f32 v128, v141, v128
	v_or_b32_e32 v141, 48, v138
	v_cvt_pk_bf16_f32 v129, v129, v130
	v_cvt_pk_bf16_f32 v130, v158, v159
	v_cvt_pk_bf16_f32 v131, v160, v131
	global_store_dwordx4 v[150:151], v[128:131], off offset:256
	s_nop 1
	v_add_f32_e32 v128, v72, v176
	v_add_f32_e32 v129, v73, v177
	v_add_f32_e32 v130, v74, v178
	v_mul_f32_e32 v128, 0xbfb8aa3b, v128
	v_mul_f32_e32 v129, 0xbfb8aa3b, v129
	v_mul_f32_e32 v130, 0xbfb8aa3b, v130
	v_exp_f32_e32 v128, v128
	v_exp_f32_e32 v129, v129
	v_exp_f32_e32 v130, v130
	v_add_f32_e32 v150, v76, v180
	v_add_f32_e32 v128, 1.0, v128
	v_add_f32_e32 v129, 1.0, v129
	v_add_f32_e32 v130, 1.0, v130
	v_rcp_f32_e32 v151, v128
	v_add_f32_e32 v128, v77, v181
; __device__ __forceinline__ float sigmoidf_(float x) { return __builtin_amdgcn_rcpf(1.0f + __expf(-x)); }
; __device__ __forceinline__ u32x4 pack8(const f32x4 v0, const f32x4 v1) { u32x4 w; w.x = cvt_pk_bf16(v0[0], v0[1]); w.y = cvt_pk_bf16(v0[2], v0[3]); w.z = cvt_pk_bf16(v1[0], v1[1]); w.w = cvt_pk_bf16(v1[2], v1[3]); return w; }
;     __device__ __forceinline__ void operator()(const Acc& acc, const Unit& u, int wr, int wc, int fr, int fq) const {
;     ...
;             for (int ai = 0; ai < 2; ++ai)
; #pragma unroll
;                 for (int m = 0; m < 4; ++m) { const int row = row0 + ai * HALF + m * 16;
; #pragma unroll
;                     for (int bj = 0; bj < 2; ++bj) { const int col = colt + bj * HALF + cw; const f32x4 b0 = *(const f32x4*)(gbias + col), b1 = *(const f32x4*)(gbias + col + 4); f32x4 v[2];
; #pragma unroll
;                         for (int j = 0; j < 4; ++j) { v[0][j] = sigmoidf_(acc[ai][bj][m][0][j] + b0[j]); v[1][j] = sigmoidf_(acc[ai][bj][m][1][j] + b1[j]); }
;                         *(u32x4*)(GT + (size_t)row * GTP + col) = pack8(v[0], v[1]); } }
	v_rcp_f32_e32 v158, v129
	v_add_f32_e32 v129, v78, v182
	v_rcp_f32_e32 v159, v130
	v_add_f32_e32 v130, v79, v183
	v_mul_f32_e32 v150, 0xbfb8aa3b, v150
	v_mul_f32_e32 v128, 0xbfb8aa3b, v128
	v_mul_f32_e32 v129, 0xbfb8aa3b, v129
	v_mul_f32_e32 v130, 0xbfb8aa3b, v130
	v_add_f32_e32 v131, v75, v179
	v_exp_f32_e32 v150, v150
	v_exp_f32_e32 v128, v128
	v_exp_f32_e32 v129, v129
	v_exp_f32_e32 v130, v130
	v_mul_f32_e32 v131, 0xbfb8aa3b, v131
	v_exp_f32_e32 v131, v131
	v_add_f32_e32 v150, 1.0, v150
	v_add_f32_e32 v128, 1.0, v128
	v_add_f32_e32 v129, 1.0, v129
	v_add_f32_e32 v130, 1.0, v130
	v_rcp_f32_e32 v150, v150
	v_rcp_f32_e32 v128, v128
	v_rcp_f32_e32 v129, v129
	v_rcp_f32_e32 v130, v130
	v_add_f32_e32 v131, 1.0, v131
	v_rcp_f32_e32 v131, v131
	v_cvt_pk_bf16_f32 v128, v150, v128
	v_cvt_pk_bf16_f32 v129, v129, v130
	v_cvt_pk_bf16_f32 v130, v151, v158
	v_mad_i64_i32 v[150:151], s[22:23], v141, s6, v[146:147]
	v_cvt_pk_bf16_f32 v131, v159, v131
	v_lshl_add_u64 v[150:151], v[150:151], 0, v[148:149]
	global_store_dwordx4 v[150:151], v[128:131], off
	s_nop 1
	v_add_f32_e32 v128, v64, v184
	v_add_f32_e32 v129, v65, v185
	v_add_f32_e32 v130, v66, v186
	v_mul_f32_e32 v128, 0xbfb8aa3b, v128
	v_mul_f32_e32 v129, 0xbfb8aa3b, v129
	v_mul_f32_e32 v130, 0xbfb8aa3b, v130
	v_exp_f32_e32 v128, v128
	v_exp_f32_e32 v129, v129
	v_exp_f32_e32 v130, v130
	v_add_f32_e32 v141, v68, v188
	v_add_f32_e32 v128, 1.0, v128
	v_add_f32_e32 v129, 1.0, v129
	v_add_f32_e32 v130, 1.0, v130
	v_rcp_f32_e32 v158, v128
	v_add_f32_e32 v128, v69, v189
	v_rcp_f32_e32 v159, v129
	v_add_f32_e32 v129, v70, v190
	v_rcp_f32_e32 v160, v130
	v_add_f32_e32 v130, v71, v191
	v_add_f32_e32 v131, v67, v187
	v_mul_f32_e32 v141, 0xbfb8aa3b, v141
	v_mul_f32_e32 v128, 0xbfb8aa3b, v128
	v_mul_f32_e32 v129, 0xbfb8aa3b, v129
	v_mul_f32_e32 v130, 0xbfb8aa3b, v130
	v_mul_f32_e32 v131, 0xbfb8aa3b, v131
	v_exp_f32_e32 v141, v141
	v_exp_f32_e32 v128, v128
	v_exp_f32_e32 v129, v129
	v_exp_f32_e32 v130, v130
	v_exp_f32_e32 v131, v131
	v_add_f32_e32 v141, 1.0, v141
	v_add_f32_e32 v128, 1.0, v128
	v_add_f32_e32 v129, 1.0, v129
	v_add_f32_e32 v130, 1.0, v130
	v_add_f32_e32 v131, 1.0, v131
	v_rcp_f32_e32 v141, v141
	v_rcp_f32_e32 v128, v128
	v_rcp_f32_e32 v129, v129
	v_rcp_f32_e32 v130, v130
	v_rcp_f32_e32 v131, v131
	v_cvt_pk_bf16_f32 v128, v141, v128
	v_add_u32_e32 v141, 0x80, v138
	v_cvt_pk_bf16_f32 v129, v129, v130
	v_cvt_pk_bf16_f32 v130, v158, v159
	v_cvt_pk_bf16_f32 v131, v160, v131
	global_store_dwordx4 v[150:151], v[128:131], off offset:256
	s_nop 1
	v_add_f32_e32 v128, v56, v176
	v_add_f32_e32 v129, v57, v177
	v_add_f32_e32 v130, v58, v178
	v_mul_f32_e32 v128, 0xbfb8aa3b, v128
	v_mul_f32_e32 v129, 0xbfb8aa3b, v129
	v_mul_f32_e32 v130, 0xbfb8aa3b, v130
	v_exp_f32_e32 v128, v128
	v_exp_f32_e32 v129, v129
	v_exp_f32_e32 v130, v130
	v_add_f32_e32 v150, v60, v180
	v_add_f32_e32 v128, 1.0, v128
	v_add_f32_e32 v129, 1.0, v129
	v_add_f32_e32 v130, 1.0, v130
	v_rcp_f32_e32 v151, v128
	v_add_f32_e32 v128, v61, v181
	v_rcp_f32_e32 v158, v129
	v_add_f32_e32 v129, v62, v182
	v_rcp_f32_e32 v159, v130
	v_add_f32_e32 v130, v63, v183
	v_mul_f32_e32 v150, 0xbfb8aa3b, v150
	v_mul_f32_e32 v128, 0xbfb8aa3b, v128
	v_mul_f32_e32 v129, 0xbfb8aa3b, v129
	v_mul_f32_e32 v130, 0xbfb8aa3b, v130
	v_add_f32_e32 v131, v59, v179
	v_exp_f32_e32 v150, v150
	v_exp_f32_e32 v128, v128
	v_exp_f32_e32 v129, v129
	v_exp_f32_e32 v130, v130
	v_mul_f32_e32 v131, 0xbfb8aa3b, v131
	v_exp_f32_e32 v131, v131
	v_add_f32_e32 v150, 1.0, v150
	v_add_f32_e32 v128, 1.0, v128
	v_add_f32_e32 v129, 1.0, v129
	v_add_f32_e32 v130, 1.0, v130
	v_rcp_f32_e32 v150, v150
	v_rcp_f32_e32 v128, v128
	v_rcp_f32_e32 v129, v129
	v_rcp_f32_e32 v130, v130
	v_add_f32_e32 v131, 1.0, v131
	v_rcp_f32_e32 v131, v131
	v_cvt_pk_bf16_f32 v128, v150, v128
	v_cvt_pk_bf16_f32 v129, v129, v130
	v_cvt_pk_bf16_f32 v130, v151, v158
	v_mad_i64_i32 v[150:151], s[22:23], v141, s6, v[146:147]
	v_cvt_pk_bf16_f32 v131, v159, v131
	v_lshl_add_u64 v[150:151], v[150:151], 0, v[148:149]
	global_store_dwordx4 v[150:151], v[128:131], off
	s_nop 1
	v_add_f32_e32 v128, v48, v184
	v_add_f32_e32 v129, v49, v185
	v_add_f32_e32 v130, v50, v186
	v_mul_f32_e32 v128, 0xbfb8aa3b, v128
	v_mul_f32_e32 v129, 0xbfb8aa3b, v129
	v_mul_f32_e32 v130, 0xbfb8aa3b, v130
	v_exp_f32_e32 v128, v128
	v_exp_f32_e32 v129, v129
	v_exp_f32_e32 v130, v130
	v_add_f32_e32 v141, v52, v188
	v_add_f32_e32 v128, 1.0, v128
	v_add_f32_e32 v129, 1.0, v129
	v_add_f32_e32 v130, 1.0, v130
	v_rcp_f32_e32 v158, v128
	v_add_f32_e32 v128, v53, v189
	v_rcp_f32_e32 v159, v129
	v_add_f32_e32 v129, v54, v190
	v_rcp_f32_e32 v160, v130
	v_add_f32_e32 v130, v55, v191
	v_add_f32_e32 v131, v51, v187
	v_mul_f32_e32 v141, 0xbfb8aa3b, v141
	v_mul_f32_e32 v128, 0xbfb8aa3b, v128
	v_mul_f32_e32 v129, 0xbfb8aa3b, v129
	v_mul_f32_e32 v130, 0xbfb8aa3b, v130
	v_mul_f32_e32 v131, 0xbfb8aa3b, v131
	v_exp_f32_e32 v141, v141
	v_exp_f32_e32 v128, v128
	v_exp_f32_e32 v129, v129
	v_exp_f32_e32 v130, v130
	v_exp_f32_e32 v131, v131
	v_add_f32_e32 v141, 1.0, v141
	v_add_f32_e32 v128, 1.0, v128
	v_add_f32_e32 v129, 1.0, v129
	v_add_f32_e32 v130, 1.0, v130
	v_add_f32_e32 v131, 1.0, v131
	v_rcp_f32_e32 v141, v141
	v_rcp_f32_e32 v128, v128
	v_rcp_f32_e32 v129, v129
	v_rcp_f32_e32 v130, v130
	v_rcp_f32_e32 v131, v131
	v_cvt_pk_bf16_f32 v128, v141, v128
	v_add_u32_e32 v141, 0x90, v138
	v_cvt_pk_bf16_f32 v129, v129, v130
	v_cvt_pk_bf16_f32 v130, v158, v159
	v_cvt_pk_bf16_f32 v131, v160, v131
	global_store_dwordx4 v[150:151], v[128:131], off offset:256
	s_nop 1
	v_add_f32_e32 v128, v40, v176
	v_add_f32_e32 v129, v41, v177
	v_add_f32_e32 v130, v42, v178
	v_mul_f32_e32 v128, 0xbfb8aa3b, v128
; __device__ __forceinline__ float sigmoidf_(float x) { return __builtin_amdgcn_rcpf(1.0f + __expf(-x)); }
; __device__ __forceinline__ u32x4 pack8(const f32x4 v0, const f32x4 v1) { u32x4 w; w.x = cvt_pk_bf16(v0[0], v0[1]); w.y = cvt_pk_bf16(v0[2], v0[3]); w.z = cvt_pk_bf16(v1[0], v1[1]); w.w = cvt_pk_bf16(v1[2], v1[3]); return w; }
;     __device__ __forceinline__ void operator()(const Acc& acc, const Unit& u, int wr, int wc, int fr, int fq) const {
;     ...
;             for (int ai = 0; ai < 2; ++ai)
; #pragma unroll
;                 for (int m = 0; m < 4; ++m) { const int row = row0 + ai * HALF + m * 16;
; #pragma unroll
;                     for (int bj = 0; bj < 2; ++bj) { const int col = colt + bj * HALF + cw; const f32x4 b0 = *(const f32x4*)(gbias + col), b1 = *(const f32x4*)(gbias + col + 4); f32x4 v[2];
; #pragma unroll
;                         for (int j = 0; j < 4; ++j) { v[0][j] = sigmoidf_(acc[ai][bj][m][0][j] + b0[j]); v[1][j] = sigmoidf_(acc[ai][bj][m][1][j] + b1[j]); }
;                         *(u32x4*)(GT + (size_t)row * GTP + col) = pack8(v[0], v[1]); } }
	v_mul_f32_e32 v129, 0xbfb8aa3b, v129
	v_mul_f32_e32 v130, 0xbfb8aa3b, v130
	v_exp_f32_e32 v128, v128
	v_exp_f32_e32 v129, v129
	v_exp_f32_e32 v130, v130
	v_add_f32_e32 v150, v44, v180
	v_add_f32_e32 v128, 1.0, v128
	v_add_f32_e32 v129, 1.0, v129
	v_add_f32_e32 v130, 1.0, v130
	v_rcp_f32_e32 v151, v128
	v_add_f32_e32 v128, v45, v181
	v_rcp_f32_e32 v158, v129
	v_add_f32_e32 v129, v46, v182
	v_rcp_f32_e32 v159, v130
	v_add_f32_e32 v130, v47, v183
	v_mul_f32_e32 v150, 0xbfb8aa3b, v150
	v_mul_f32_e32 v128, 0xbfb8aa3b, v128
	v_mul_f32_e32 v129, 0xbfb8aa3b, v129
	v_mul_f32_e32 v130, 0xbfb8aa3b, v130
	v_add_f32_e32 v131, v43, v179
	v_exp_f32_e32 v150, v150
	v_exp_f32_e32 v128, v128
	v_exp_f32_e32 v129, v129
	v_exp_f32_e32 v130, v130
	v_mul_f32_e32 v131, 0xbfb8aa3b, v131
	v_exp_f32_e32 v131, v131
	v_add_f32_e32 v150, 1.0, v150
	v_add_f32_e32 v128, 1.0, v128
	v_add_f32_e32 v129, 1.0, v129
	v_add_f32_e32 v130, 1.0, v130
	v_rcp_f32_e32 v150, v150
	v_rcp_f32_e32 v128, v128
	v_rcp_f32_e32 v129, v129
	v_rcp_f32_e32 v130, v130
	v_add_f32_e32 v131, 1.0, v131
	v_rcp_f32_e32 v131, v131
	v_cvt_pk_bf16_f32 v128, v150, v128
	v_cvt_pk_bf16_f32 v129, v129, v130
	v_cvt_pk_bf16_f32 v130, v151, v158
	v_mad_i64_i32 v[150:151], s[22:23], v141, s6, v[146:147]
	v_cvt_pk_bf16_f32 v131, v159, v131
	v_lshl_add_u64 v[150:151], v[150:151], 0, v[148:149]
	global_store_dwordx4 v[150:151], v[128:131], off
	s_nop 1
	v_add_f32_e32 v128, v32, v184
	v_add_f32_e32 v129, v33, v185
	v_add_f32_e32 v130, v34, v186
	v_mul_f32_e32 v128, 0xbfb8aa3b, v128
	v_mul_f32_e32 v129, 0xbfb8aa3b, v129
	v_mul_f32_e32 v130, 0xbfb8aa3b, v130
	v_exp_f32_e32 v128, v128
	v_exp_f32_e32 v129, v129
	v_exp_f32_e32 v130, v130
	v_add_f32_e32 v141, v36, v188
	v_add_f32_e32 v128, 1.0, v128
	v_add_f32_e32 v129, 1.0, v129
	v_add_f32_e32 v130, 1.0, v130
	v_rcp_f32_e32 v158, v128
	v_add_f32_e32 v128, v37, v189
	v_rcp_f32_e32 v159, v129
	v_add_f32_e32 v129, v38, v190
	v_rcp_f32_e32 v160, v130
	v_add_f32_e32 v130, v39, v191
	v_add_f32_e32 v131, v35, v187
	v_mul_f32_e32 v141, 0xbfb8aa3b, v141
	v_mul_f32_e32 v128, 0xbfb8aa3b, v128
	v_mul_f32_e32 v129, 0xbfb8aa3b, v129
	v_mul_f32_e32 v130, 0xbfb8aa3b, v130
	v_mul_f32_e32 v131, 0xbfb8aa3b, v131
	v_exp_f32_e32 v141, v141
	v_exp_f32_e32 v128, v128
	v_exp_f32_e32 v129, v129
	v_exp_f32_e32 v130, v130
	v_exp_f32_e32 v131, v131
	v_add_f32_e32 v141, 1.0, v141
	v_add_f32_e32 v128, 1.0, v128
	v_add_f32_e32 v129, 1.0, v129
	v_add_f32_e32 v130, 1.0, v130
	v_add_f32_e32 v131, 1.0, v131
	v_rcp_f32_e32 v141, v141
	v_rcp_f32_e32 v128, v128
	v_rcp_f32_e32 v129, v129
	v_rcp_f32_e32 v130, v130
	v_rcp_f32_e32 v131, v131
	v_cvt_pk_bf16_f32 v128, v141, v128
	v_add_u32_e32 v141, 0xa0, v138
	v_cvt_pk_bf16_f32 v129, v129, v130
	v_cvt_pk_bf16_f32 v130, v158, v159
	v_cvt_pk_bf16_f32 v131, v160, v131
	global_store_dwordx4 v[150:151], v[128:131], off offset:256
	s_nop 1
	v_add_f32_e32 v128, v24, v176
	v_add_f32_e32 v129, v25, v177
	v_add_f32_e32 v130, v26, v178
	v_mul_f32_e32 v128, 0xbfb8aa3b, v128
	v_mul_f32_e32 v129, 0xbfb8aa3b, v129
	v_mul_f32_e32 v130, 0xbfb8aa3b, v130
	v_exp_f32_e32 v128, v128
	v_exp_f32_e32 v129, v129
	v_exp_f32_e32 v130, v130
	v_add_f32_e32 v150, v28, v180
	v_add_f32_e32 v128, 1.0, v128
	v_add_f32_e32 v129, 1.0, v129
	v_add_f32_e32 v130, 1.0, v130
	v_rcp_f32_e32 v151, v128
	v_add_f32_e32 v128, v29, v181
	v_rcp_f32_e32 v158, v129
	v_add_f32_e32 v129, v30, v182
	v_rcp_f32_e32 v159, v130
	v_add_f32_e32 v130, v31, v183
	v_mul_f32_e32 v150, 0xbfb8aa3b, v150
	v_mul_f32_e32 v128, 0xbfb8aa3b, v128
	v_mul_f32_e32 v129, 0xbfb8aa3b, v129
	v_mul_f32_e32 v130, 0xbfb8aa3b, v130
	v_add_f32_e32 v131, v27, v179
	v_exp_f32_e32 v150, v150
	v_exp_f32_e32 v128, v128
	v_exp_f32_e32 v129, v129
	v_exp_f32_e32 v130, v130
	v_mul_f32_e32 v131, 0xbfb8aa3b, v131
	v_exp_f32_e32 v131, v131
	v_add_f32_e32 v150, 1.0, v150
	v_add_f32_e32 v128, 1.0, v128
	v_add_f32_e32 v129, 1.0, v129
	v_add_f32_e32 v130, 1.0, v130
	v_rcp_f32_e32 v150, v150
	v_rcp_f32_e32 v128, v128
	v_rcp_f32_e32 v129, v129
	v_rcp_f32_e32 v130, v130
	v_add_f32_e32 v131, 1.0, v131
	v_rcp_f32_e32 v131, v131
	v_cvt_pk_bf16_f32 v128, v150, v128
	v_cvt_pk_bf16_f32 v129, v129, v130
	v_cvt_pk_bf16_f32 v130, v151, v158
	v_mad_i64_i32 v[150:151], s[22:23], v141, s6, v[146:147]
	v_cvt_pk_bf16_f32 v131, v159, v131
	v_lshl_add_u64 v[150:151], v[150:151], 0, v[148:149]
	global_store_dwordx4 v[150:151], v[128:131], off
	s_nop 1
; __device__ __forceinline__ float sigmoidf_(float x) { return __builtin_amdgcn_rcpf(1.0f + __expf(-x)); }
; __device__ __forceinline__ u32x4 pack8(const f32x4 v0, const f32x4 v1) { u32x4 w; w.x = cvt_pk_bf16(v0[0], v0[1]); w.y = cvt_pk_bf16(v0[2], v0[3]); w.z = cvt_pk_bf16(v1[0], v1[1]); w.w = cvt_pk_bf16(v1[2], v1[3]); return w; }
;     __device__ __forceinline__ void operator()(const Acc& acc, const Unit& u, int wr, int wc, int fr, int fq) const {
;     ...
;             for (int ai = 0; ai < 2; ++ai)
; #pragma unroll
;                 for (int m = 0; m < 4; ++m) { const int row = row0 + ai * HALF + m * 16;
; #pragma unroll
;                     for (int bj = 0; bj < 2; ++bj) { const int col = colt + bj * HALF + cw; const f32x4 b0 = *(const f32x4*)(gbias + col), b1 = *(const f32x4*)(gbias + col + 4); f32x4 v[2];
; #pragma unroll
;                         for (int j = 0; j < 4; ++j) { v[0][j] = sigmoidf_(acc[ai][bj][m][0][j] + b0[j]); v[1][j] = sigmoidf_(acc[ai][bj][m][1][j] + b1[j]); }
;                         *(u32x4*)(GT + (size_t)row * GTP + col) = pack8(v[0], v[1]); } }
	v_add_f32_e32 v128, v16, v184
	v_add_f32_e32 v129, v17, v185
	v_add_f32_e32 v130, v18, v186
	v_mul_f32_e32 v128, 0xbfb8aa3b, v128
	v_mul_f32_e32 v129, 0xbfb8aa3b, v129
	v_mul_f32_e32 v130, 0xbfb8aa3b, v130
	v_exp_f32_e32 v128, v128
	v_exp_f32_e32 v129, v129
	v_exp_f32_e32 v130, v130
	v_add_f32_e32 v141, v20, v188
	v_add_f32_e32 v128, 1.0, v128
	v_add_f32_e32 v129, 1.0, v129
	v_add_f32_e32 v130, 1.0, v130
	v_rcp_f32_e32 v158, v128
	v_add_f32_e32 v128, v21, v189
	v_rcp_f32_e32 v159, v129
	v_add_f32_e32 v129, v22, v190
	v_rcp_f32_e32 v160, v130
	v_add_f32_e32 v130, v23, v191
	v_add_f32_e32 v131, v19, v187
	v_mul_f32_e32 v141, 0xbfb8aa3b, v141
	v_mul_f32_e32 v128, 0xbfb8aa3b, v128
	v_mul_f32_e32 v129, 0xbfb8aa3b, v129
	v_mul_f32_e32 v130, 0xbfb8aa3b, v130
	v_mul_f32_e32 v131, 0xbfb8aa3b, v131
	v_exp_f32_e32 v141, v141
	v_exp_f32_e32 v128, v128
	v_exp_f32_e32 v129, v129
	v_exp_f32_e32 v130, v130
	v_exp_f32_e32 v131, v131
	v_add_f32_e32 v141, 1.0, v141
	v_add_f32_e32 v128, 1.0, v128
	v_add_f32_e32 v129, 1.0, v129
	v_add_f32_e32 v130, 1.0, v130
	v_add_f32_e32 v131, 1.0, v131
	v_rcp_f32_e32 v141, v141
	v_rcp_f32_e32 v128, v128
	v_rcp_f32_e32 v129, v129
	v_rcp_f32_e32 v130, v130
	v_rcp_f32_e32 v131, v131
	v_cvt_pk_bf16_f32 v128, v141, v128
	v_add_u32_e32 v141, 0xb0, v138
	v_cvt_pk_bf16_f32 v129, v129, v130
	v_cvt_pk_bf16_f32 v130, v158, v159
	v_cvt_pk_bf16_f32 v131, v160, v131
	global_store_dwordx4 v[150:151], v[128:131], off offset:256
	s_nop 1
	v_mad_i64_i32 v[146:147], s[22:23], v141, s6, v[146:147]
	v_lshl_add_u64 v[146:147], v[146:147], 0, v[148:149]
	v_add_f32_e32 v128, v8, v176
	v_add_f32_e32 v129, v9, v177
	v_add_f32_e32 v130, v10, v178
	v_mul_f32_e32 v128, 0xbfb8aa3b, v128
	v_mul_f32_e32 v129, 0xbfb8aa3b, v129
	v_mul_f32_e32 v130, 0xbfb8aa3b, v130
	v_exp_f32_e32 v128, v128
	v_exp_f32_e32 v129, v129
	v_exp_f32_e32 v130, v130
	v_add_f32_e32 v150, v12, v180
	v_add_f32_e32 v128, 1.0, v128
	v_add_f32_e32 v129, 1.0, v129
	v_add_f32_e32 v130, 1.0, v130
	v_rcp_f32_e32 v151, v128
	v_add_f32_e32 v128, v13, v181
	v_rcp_f32_e32 v158, v129
	v_add_f32_e32 v129, v14, v182
	v_rcp_f32_e32 v159, v130
	v_add_f32_e32 v130, v15, v183
	v_add_f32_e32 v131, v11, v179
	v_mul_f32_e32 v150, 0xbfb8aa3b, v150
	v_mul_f32_e32 v128, 0xbfb8aa3b, v128
	v_mul_f32_e32 v129, 0xbfb8aa3b, v129
	v_mul_f32_e32 v130, 0xbfb8aa3b, v130
	v_mul_f32_e32 v131, 0xbfb8aa3b, v131
	v_exp_f32_e32 v150, v150
	v_exp_f32_e32 v128, v128
	v_exp_f32_e32 v129, v129
	v_exp_f32_e32 v130, v130
	v_exp_f32_e32 v131, v131
	v_add_f32_e32 v150, 1.0, v150
	v_add_f32_e32 v128, 1.0, v128
	v_add_f32_e32 v129, 1.0, v129
	v_add_f32_e32 v130, 1.0, v130
	v_add_f32_e32 v131, 1.0, v131
	v_rcp_f32_e32 v150, v150
	v_rcp_f32_e32 v128, v128
	v_rcp_f32_e32 v129, v129
	v_rcp_f32_e32 v130, v130
	v_rcp_f32_e32 v131, v131
	v_cvt_pk_bf16_f32 v128, v150, v128
	v_cvt_pk_bf16_f32 v129, v129, v130
	v_cvt_pk_bf16_f32 v130, v151, v158
	v_cvt_pk_bf16_f32 v131, v159, v131
	global_store_dwordx4 v[146:147], v[128:131], off
	s_nop 1
	v_add_f32_e32 v128, v0, v184
	v_add_f32_e32 v129, v1, v185
	v_add_f32_e32 v130, v2, v186
	v_mul_f32_e32 v128, 0xbfb8aa3b, v128
	v_mul_f32_e32 v129, 0xbfb8aa3b, v129
	v_mul_f32_e32 v130, 0xbfb8aa3b, v130
	v_exp_f32_e32 v128, v128
	v_exp_f32_e32 v129, v129
	v_exp_f32_e32 v130, v130
	v_add_f32_e32 v141, v4, v188
	v_add_f32_e32 v128, 1.0, v128
	v_add_f32_e32 v129, 1.0, v129
	v_add_f32_e32 v130, 1.0, v130
	v_rcp_f32_e32 v144, v128
	v_add_f32_e32 v128, v5, v189
	v_rcp_f32_e32 v145, v129
	v_add_f32_e32 v129, v6, v190
	v_rcp_f32_e32 v148, v130
	v_add_f32_e32 v130, v7, v191
	v_add_f32_e32 v131, v3, v187
	v_mul_f32_e32 v141, 0xbfb8aa3b, v141
	v_mul_f32_e32 v128, 0xbfb8aa3b, v128
	v_mul_f32_e32 v129, 0xbfb8aa3b, v129
	v_mul_f32_e32 v130, 0xbfb8aa3b, v130
	v_mul_f32_e32 v131, 0xbfb8aa3b, v131
	v_exp_f32_e32 v141, v141
	v_exp_f32_e32 v128, v128
	v_exp_f32_e32 v129, v129
	v_exp_f32_e32 v130, v130
	v_exp_f32_e32 v131, v131
	v_add_f32_e32 v141, 1.0, v141
	v_add_f32_e32 v128, 1.0, v128
	v_add_f32_e32 v129, 1.0, v129
	v_add_f32_e32 v130, 1.0, v130
	v_add_f32_e32 v131, 1.0, v131
	v_rcp_f32_e32 v141, v141
	v_rcp_f32_e32 v128, v128
	v_rcp_f32_e32 v129, v129
	v_rcp_f32_e32 v130, v130
	v_rcp_f32_e32 v131, v131
	v_cvt_pk_bf16_f32 v128, v141, v128
	v_cvt_pk_bf16_f32 v129, v129, v130
	v_cvt_pk_bf16_f32 v130, v144, v145
	v_cvt_pk_bf16_f32 v131, v148, v131
	global_store_dwordx4 v[146:147], v[128:131], off offset:256

; __device__ __forceinline__ u32x4 pack8(const f32x4 v0, const f32x4 v1) { u32x4 w; w.x = cvt_pk_bf16(v0[0], v0[1]); w.y = cvt_pk_bf16(v0[2], v0[3]); w.z = cvt_pk_bf16(v1[0], v1[1]); w.w = cvt_pk_bf16(v1[2], v1[3]); return w; }
;     __device__ __forceinline__ void operator()(const Acc& acc, const Unit& u, int wr, int wc, int fr, int fq) const {
;         bf16_t* base = O + (size_t)(u.z / nh) * sb + (size_t)(u.z % nh) * sh;
;         const int row0 = u.pm * BM + wr * 64 + fr, col0 = u.pn * BM + wc * 32 + 8 * fq;
; #pragma unroll
;         for (int ai = 0; ai < 2; ++ai)
; #pragma unroll
;             for (int m = 0; m < 4; ++m) { const int row = row0 + ai * HALF + m * 16; float sc = scale; if (rss) sc *= rsqrtf(rss[row] * rinv + RMS_EPS);
;                 bf16_t* rowp = base + (size_t)row * ldc + col0;
; #pragma unroll
;                 for (int bj = 0; bj < 2; ++bj) *(u32x4*)(rowp + bj * HALF) = pack8(acc[ai][bj][m][0] * sc, acc[ai][bj][m][1] * sc); }
.LBB0_382:
	v_mbcnt_lo_u32_b32 v128, -1, 0
	v_mbcnt_hi_u32_b32 v128, -1, v128
	s_lshl_b32 s13, s41, 8
	v_ashrrev_i32_e32 v134, 1, v128
	v_and_or_b32 v128, v128, 15, s1
	v_lshl_add_u32 v140, s40, 8, v128
	v_ashrrev_i32_e32 v141, 31, v140
	v_lshl_add_u64 v[136:137], v[140:141], 2, s[8:9]
	global_load_dword v128, v[136:137], off
	global_load_dword v176, v[136:137], off offset:64
	global_load_dword v177, v[136:137], off offset:128
	global_load_dword v178, v[136:137], off offset:192
	global_load_dword v179, v[136:137], off offset:512
	global_load_dword v180, v[136:137], off offset:576
	global_load_dword v181, v[136:137], off offset:640
	global_load_dword v182, v[136:137], off offset:704
	v_and_b32_e32 v134, -8, v134
	s_or_b32 s13, s13, s33
	v_add_u32_e32 v134, s13, v134
	v_ashrrev_i32_e32 v135, 31, v134
	v_lshl_add_u64 v[138:139], v[134:135], 1, s[6:7]
	s_mov_b32 s13, 0x100000
	s_mov_b64 s[40:41], 0x100000
	s_waitcnt vmcnt(0)
	v_fmamk_f32 v128, v128, 0x3b000000, v143
	v_cmp_gt_f32_e32 vcc, s58, v128
	v_mul_f32_e32 v134, 0x4b800000, v128
	s_nop 0
	v_cndmask_b32_e32 v128, v128, v134, vcc
	v_rsq_f32_e32 v128, v128
	s_nop 0
	v_mul_f32_e32 v134, 0x45800000, v128
	v_cndmask_b32_e32 v128, v128, v134, vcc
	v_lshlrev_b64 v[134:135], 13, v[140:141]
	v_pk_mul_f32 v[126:127], v[126:127], v[128:129] op_sel_hi:[1,0]
	v_pk_mul_f32 v[124:125], v[124:125], v[128:129] op_sel_hi:[1,0]
	v_pk_mul_f32 v[144:145], v[122:123], v[128:129] op_sel_hi:[1,0]
	v_pk_mul_f32 v[122:123], v[120:121], v[128:129] op_sel_hi:[1,0]
	v_lshl_add_u64 v[134:135], v[138:139], 0, v[134:135]
	v_cvt_pk_bf16_f32 v120, v124, v125
	v_cvt_pk_bf16_f32 v121, v126, v127
	v_cvt_pk_bf16_f32 v122, v122, v123
	v_cvt_pk_bf16_f32 v123, v144, v145
	global_store_dwordx4 v[134:135], v[120:123], off
	v_pk_mul_f32 v[118:119], v[118:119], v[128:129] op_sel_hi:[1,0]
	v_pk_mul_f32 v[116:117], v[116:117], v[128:129] op_sel_hi:[1,0]
	v_pk_mul_f32 v[120:121], v[114:115], v[128:129] op_sel_hi:[1,0]
	v_pk_mul_f32 v[114:115], v[112:113], v[128:129] op_sel_hi:[1,0]
	v_cvt_pk_bf16_f32 v112, v116, v117
	v_cvt_pk_bf16_f32 v113, v118, v119
	v_cvt_pk_bf16_f32 v114, v114, v115
	v_cvt_pk_bf16_f32 v115, v120, v121
	global_store_dwordx4 v[134:135], v[112:115], off offset:256
	s_nop 1
	v_or_b32_e32 v112, 16, v140
	v_ashrrev_i32_e32 v113, 31, v112
	v_lshl_add_u64 v[114:115], v[112:113], 2, s[8:9]
	v_mov_b32_e32 v114, v176
	v_lshlrev_b64 v[112:113], 13, v[112:113]
	v_lshl_add_u64 v[112:113], v[138:139], 0, v[112:113]
	v_fmamk_f32 v114, v114, 0x3b000000, v143
	v_cmp_gt_f32_e32 vcc, s58, v114
	v_mul_f32_e32 v115, 0x4b800000, v114
	s_nop 0
	v_cndmask_b32_e32 v114, v114, v115, vcc
	v_rsq_f32_e32 v114, v114
	s_nop 0
	v_mul_f32_e32 v115, 0x45800000, v114
	v_cndmask_b32_e32 v114, v114, v115, vcc
	v_pk_mul_f32 v[110:111], v[110:111], v[114:115] op_sel_hi:[1,0]
	v_pk_mul_f32 v[108:109], v[108:109], v[114:115] op_sel_hi:[1,0]
	v_pk_mul_f32 v[116:117], v[106:107], v[114:115] op_sel_hi:[1,0]
	v_pk_mul_f32 v[106:107], v[104:105], v[114:115] op_sel_hi:[1,0]
	v_cvt_pk_bf16_f32 v104, v108, v109
	v_cvt_pk_bf16_f32 v105, v110, v111
	v_cvt_pk_bf16_f32 v106, v106, v107
	v_cvt_pk_bf16_f32 v107, v116, v117
	global_store_dwordx4 v[112:113], v[104:107], off
	v_pk_mul_f32 v[102:103], v[102:103], v[114:115] op_sel_hi:[1,0]
	v_pk_mul_f32 v[100:101], v[100:101], v[114:115] op_sel_hi:[1,0]
	v_pk_mul_f32 v[104:105], v[98:99], v[114:115] op_sel_hi:[1,0]
	v_pk_mul_f32 v[98:99], v[96:97], v[114:115] op_sel_hi:[1,0]
	v_cvt_pk_bf16_f32 v96, v100, v101
	v_cvt_pk_bf16_f32 v97, v102, v103
	v_cvt_pk_bf16_f32 v98, v98, v99
	v_cvt_pk_bf16_f32 v99, v104, v105
	global_store_dwordx4 v[112:113], v[96:99], off offset:256
	s_nop 1
	v_or_b32_e32 v96, 32, v140
	v_ashrrev_i32_e32 v97, 31, v96
	v_lshl_add_u64 v[98:99], v[96:97], 2, s[8:9]
	v_mov_b32_e32 v98, v177
	v_lshlrev_b64 v[96:97], 13, v[96:97]
	v_lshl_add_u64 v[96:97], v[138:139], 0, v[96:97]
	v_fmamk_f32 v98, v98, 0x3b000000, v143
	v_cmp_gt_f32_e32 vcc, s58, v98
	v_mul_f32_e32 v99, 0x4b800000, v98
	s_nop 0
	v_cndmask_b32_e32 v98, v98, v99, vcc
	v_rsq_f32_e32 v98, v98
	s_nop 0
	v_mul_f32_e32 v99, 0x45800000, v98
	v_cndmask_b32_e32 v98, v98, v99, vcc
	v_pk_mul_f32 v[94:95], v[94:95], v[98:99] op_sel_hi:[1,0]
	v_pk_mul_f32 v[92:93], v[92:93], v[98:99] op_sel_hi:[1,0]
	v_pk_mul_f32 v[100:101], v[90:91], v[98:99] op_sel_hi:[1,0]
	v_pk_mul_f32 v[90:91], v[88:89], v[98:99] op_sel_hi:[1,0]
	v_cvt_pk_bf16_f32 v88, v92, v93
	v_cvt_pk_bf16_f32 v89, v94, v95
	v_cvt_pk_bf16_f32 v90, v90, v91
	v_cvt_pk_bf16_f32 v91, v100, v101
	global_store_dwordx4 v[96:97], v[88:91], off
	v_pk_mul_f32 v[86:87], v[86:87], v[98:99] op_sel_hi:[1,0]
	v_pk_mul_f32 v[84:85], v[84:85], v[98:99] op_sel_hi:[1,0]
	v_pk_mul_f32 v[88:89], v[82:83], v[98:99] op_sel_hi:[1,0]
	v_pk_mul_f32 v[82:83], v[80:81], v[98:99] op_sel_hi:[1,0]
	v_cvt_pk_bf16_f32 v80, v84, v85
	v_cvt_pk_bf16_f32 v81, v86, v87
	v_cvt_pk_bf16_f32 v82, v82, v83
	v_cvt_pk_bf16_f32 v83, v88, v89
	global_store_dwordx4 v[96:97], v[80:83], off offset:256
	s_nop 1
	v_or_b32_e32 v80, 48, v140
	v_ashrrev_i32_e32 v81, 31, v80
	v_lshl_add_u64 v[82:83], v[80:81], 2, s[8:9]
	v_mov_b32_e32 v82, v178
	v_lshlrev_b64 v[80:81], 13, v[80:81]
	v_lshl_add_u64 v[80:81], v[138:139], 0, v[80:81]
	v_fmamk_f32 v82, v82, 0x3b000000, v143
	v_cmp_gt_f32_e32 vcc, s58, v82
	v_mul_f32_e32 v83, 0x4b800000, v82
	s_nop 0
	v_cndmask_b32_e32 v82, v82, v83, vcc
	v_rsq_f32_e32 v82, v82
	s_nop 0
	v_mul_f32_e32 v83, 0x45800000, v82
	v_cndmask_b32_e32 v82, v82, v83, vcc
	v_pk_mul_f32 v[78:79], v[78:79], v[82:83] op_sel_hi:[1,0]
	v_pk_mul_f32 v[76:77], v[76:77], v[82:83] op_sel_hi:[1,0]
	v_pk_mul_f32 v[84:85], v[74:75], v[82:83] op_sel_hi:[1,0]
; #define PG8_BAR __builtin_amdgcn_s_barrier()
; __device__ __forceinline__ u32x4 pack8(const f32x4 v0, const f32x4 v1) { u32x4 w; w.x = cvt_pk_bf16(v0[0], v0[1]); w.y = cvt_pk_bf16(v0[2], v0[3]); w.z = cvt_pk_bf16(v1[0], v1[1]); w.w = cvt_pk_bf16(v1[2], v1[3]); return w; }
; template <class Epi>
; __device__ __forceinline__ void gemm_phase(LAS unsigned char* lds, const Gemm g, const Order& S, const Epi& E, const int wid) {
;     ...
;         cur = nxt; cA = nA; cB = nB; ++ui;
;         PG8_LANESETUP();
;         if (wr == 1) PG8_BAR;
;     __device__ __forceinline__ void operator()(const Acc& acc, const Unit& u, int wr, int wc, int fr, int fq) const {
;     ...
;         for (int ai = 0; ai < 2; ++ai)
; #pragma unroll
;             for (int m = 0; m < 4; ++m) { const int row = row0 + ai * HALF + m * 16; float sc = scale; if (rss) sc *= rsqrtf(rss[row] * rinv + RMS_EPS);
;                 bf16_t* rowp = base + (size_t)row * ldc + col0;
; #pragma unroll
;                 for (int bj = 0; bj < 2; ++bj) *(u32x4*)(rowp + bj * HALF) = pack8(acc[ai][bj][m][0] * sc, acc[ai][bj][m][1] * sc); }
	v_pk_mul_f32 v[74:75], v[72:73], v[82:83] op_sel_hi:[1,0]
	v_cvt_pk_bf16_f32 v72, v76, v77
	v_cvt_pk_bf16_f32 v73, v78, v79
	v_cvt_pk_bf16_f32 v74, v74, v75
	v_cvt_pk_bf16_f32 v75, v84, v85
	global_store_dwordx4 v[80:81], v[72:75], off
	v_pk_mul_f32 v[70:71], v[70:71], v[82:83] op_sel_hi:[1,0]
	v_pk_mul_f32 v[68:69], v[68:69], v[82:83] op_sel_hi:[1,0]
	v_pk_mul_f32 v[72:73], v[66:67], v[82:83] op_sel_hi:[1,0]
	v_pk_mul_f32 v[66:67], v[64:65], v[82:83] op_sel_hi:[1,0]
	v_cvt_pk_bf16_f32 v64, v68, v69
	v_cvt_pk_bf16_f32 v65, v70, v71
	v_cvt_pk_bf16_f32 v66, v66, v67
	v_cvt_pk_bf16_f32 v67, v72, v73
	global_store_dwordx4 v[80:81], v[64:67], off offset:256
	s_nop 1
	v_mov_b32_e32 v64, v179
	s_nop 0
	v_lshl_add_u64 v[66:67], v[134:135], 0, s[40:41]
	s_mov_b64 s[40:41], 0x120000
	v_fmamk_f32 v64, v64, 0x3b000000, v143
	v_cmp_gt_f32_e32 vcc, s58, v64
	v_mul_f32_e32 v65, 0x4b800000, v64
	s_nop 0
	v_cndmask_b32_e32 v64, v64, v65, vcc
	v_rsq_f32_e32 v64, v64
	s_nop 0
	v_mul_f32_e32 v65, 0x45800000, v64
	v_cndmask_b32_e32 v64, v64, v65, vcc
	v_pk_mul_f32 v[60:61], v[60:61], v[64:65] op_sel_hi:[1,0]
	v_pk_mul_f32 v[62:63], v[62:63], v[64:65] op_sel_hi:[1,0]
	v_pk_mul_f32 v[68:69], v[58:59], v[64:65] op_sel_hi:[1,0]
	v_pk_mul_f32 v[58:59], v[56:57], v[64:65] op_sel_hi:[1,0]
	v_cvt_pk_bf16_f32 v56, v60, v61
	v_add_co_u32_e32 v60, vcc, s13, v134
	v_cvt_pk_bf16_f32 v57, v62, v63
	v_cvt_pk_bf16_f32 v58, v58, v59
	v_cvt_pk_bf16_f32 v59, v68, v69
	v_addc_co_u32_e32 v61, vcc, 0, v135, vcc
	global_store_dwordx4 v[60:61], v[56:59], off
	v_pk_mul_f32 v[54:55], v[54:55], v[64:65] op_sel_hi:[1,0]
	v_pk_mul_f32 v[52:53], v[52:53], v[64:65] op_sel_hi:[1,0]
	v_pk_mul_f32 v[56:57], v[50:51], v[64:65] op_sel_hi:[1,0]
	v_pk_mul_f32 v[50:51], v[48:49], v[64:65] op_sel_hi:[1,0]
	v_cvt_pk_bf16_f32 v48, v52, v53
	v_cvt_pk_bf16_f32 v49, v54, v55
	v_cvt_pk_bf16_f32 v50, v50, v51
	v_cvt_pk_bf16_f32 v51, v56, v57
	global_store_dwordx4 v[66:67], v[48:51], off offset:256
	s_nop 1
	v_mov_b32_e32 v48, v180
	s_mov_b32 s13, 0x120000
	v_lshl_add_u64 v[50:51], v[134:135], 0, s[40:41]
	s_mov_b64 s[40:41], 0x140000
	v_fmamk_f32 v48, v48, 0x3b000000, v143
	v_cmp_gt_f32_e32 vcc, s58, v48
	v_mul_f32_e32 v49, 0x4b800000, v48
	s_nop 0
	v_cndmask_b32_e32 v48, v48, v49, vcc
	v_rsq_f32_e32 v48, v48
	s_nop 0
	v_mul_f32_e32 v49, 0x45800000, v48
	v_cndmask_b32_e32 v48, v48, v49, vcc
	v_pk_mul_f32 v[44:45], v[44:45], v[48:49] op_sel_hi:[1,0]
	v_pk_mul_f32 v[46:47], v[46:47], v[48:49] op_sel_hi:[1,0]
	v_pk_mul_f32 v[52:53], v[42:43], v[48:49] op_sel_hi:[1,0]
	v_pk_mul_f32 v[42:43], v[40:41], v[48:49] op_sel_hi:[1,0]
	v_cvt_pk_bf16_f32 v40, v44, v45
	v_add_co_u32_e32 v44, vcc, s13, v134
	v_cvt_pk_bf16_f32 v41, v46, v47
	v_cvt_pk_bf16_f32 v42, v42, v43
	v_cvt_pk_bf16_f32 v43, v52, v53
	v_addc_co_u32_e32 v45, vcc, 0, v135, vcc
	global_store_dwordx4 v[44:45], v[40:43], off
	v_pk_mul_f32 v[38:39], v[38:39], v[48:49] op_sel_hi:[1,0]
	v_pk_mul_f32 v[36:37], v[36:37], v[48:49] op_sel_hi:[1,0]
	v_pk_mul_f32 v[40:41], v[34:35], v[48:49] op_sel_hi:[1,0]
	v_pk_mul_f32 v[34:35], v[32:33], v[48:49] op_sel_hi:[1,0]
	v_cvt_pk_bf16_f32 v32, v36, v37
	v_cvt_pk_bf16_f32 v33, v38, v39
	v_cvt_pk_bf16_f32 v34, v34, v35
	v_cvt_pk_bf16_f32 v35, v40, v41
	global_store_dwordx4 v[50:51], v[32:35], off offset:256
	s_nop 1
	v_mov_b32_e32 v32, v181
	s_mov_b32 s13, 0x140000
	v_lshl_add_u64 v[34:35], v[134:135], 0, s[40:41]
	s_mov_b64 s[40:41], 0x160000
	v_fmamk_f32 v32, v32, 0x3b000000, v143
	v_cmp_gt_f32_e32 vcc, s58, v32
	v_mul_f32_e32 v33, 0x4b800000, v32
	s_nop 0
	v_cndmask_b32_e32 v32, v32, v33, vcc
	v_rsq_f32_e32 v32, v32
	s_nop 0
	v_mul_f32_e32 v33, 0x45800000, v32
	v_cndmask_b32_e32 v32, v32, v33, vcc
	v_pk_mul_f32 v[28:29], v[28:29], v[32:33] op_sel_hi:[1,0]
	v_pk_mul_f32 v[30:31], v[30:31], v[32:33] op_sel_hi:[1,0]
	v_pk_mul_f32 v[36:37], v[26:27], v[32:33] op_sel_hi:[1,0]
	v_pk_mul_f32 v[26:27], v[24:25], v[32:33] op_sel_hi:[1,0]
	v_cvt_pk_bf16_f32 v24, v28, v29
	v_add_co_u32_e32 v28, vcc, s13, v134
	v_cvt_pk_bf16_f32 v25, v30, v31
	v_cvt_pk_bf16_f32 v26, v26, v27
	v_cvt_pk_bf16_f32 v27, v36, v37
	v_addc_co_u32_e32 v29, vcc, 0, v135, vcc
	global_store_dwordx4 v[28:29], v[24:27], off
	v_pk_mul_f32 v[22:23], v[22:23], v[32:33] op_sel_hi:[1,0]
	v_pk_mul_f32 v[20:21], v[20:21], v[32:33] op_sel_hi:[1,0]
	v_pk_mul_f32 v[24:25], v[18:19], v[32:33] op_sel_hi:[1,0]
	v_pk_mul_f32 v[18:19], v[16:17], v[32:33] op_sel_hi:[1,0]
	v_cvt_pk_bf16_f32 v16, v20, v21
	v_cvt_pk_bf16_f32 v17, v22, v23
	v_cvt_pk_bf16_f32 v18, v18, v19
	v_cvt_pk_bf16_f32 v19, v24, v25
	global_store_dwordx4 v[34:35], v[16:19], off offset:256
	s_nop 1
	v_mov_b32_e32 v16, v182
	s_mov_b32 s13, 0x160000
	v_lshl_add_u64 v[18:19], v[134:135], 0, s[40:41]
	s_mov_b64 s[40:41], -1
	v_fmamk_f32 v16, v16, 0x3b000000, v143
	v_cmp_gt_f32_e32 vcc, s58, v16
	v_mul_f32_e32 v17, 0x4b800000, v16
	s_nop 0
	v_cndmask_b32_e32 v16, v16, v17, vcc
	v_rsq_f32_e32 v16, v16
	s_nop 0
	v_mul_f32_e32 v17, 0x45800000, v16
	v_cndmask_b32_e32 v16, v16, v17, vcc
	v_pk_mul_f32 v[12:13], v[12:13], v[16:17] op_sel_hi:[1,0]
	v_pk_mul_f32 v[14:15], v[14:15], v[16:17] op_sel_hi:[1,0]
	v_pk_mul_f32 v[20:21], v[10:11], v[16:17] op_sel_hi:[1,0]
	v_pk_mul_f32 v[10:11], v[8:9], v[16:17] op_sel_hi:[1,0]
	v_cvt_pk_bf16_f32 v8, v12, v13
	v_add_co_u32_e32 v12, vcc, s13, v134
	v_cvt_pk_bf16_f32 v9, v14, v15
	v_cvt_pk_bf16_f32 v10, v10, v11
	v_cvt_pk_bf16_f32 v11, v20, v21
	v_addc_co_u32_e32 v13, vcc, 0, v135, vcc
	global_store_dwordx4 v[12:13], v[8:11], off
	v_pk_mul_f32 v[6:7], v[6:7], v[16:17] op_sel_hi:[1,0]
	v_pk_mul_f32 v[4:5], v[4:5], v[16:17] op_sel_hi:[1,0]
	v_pk_mul_f32 v[8:9], v[2:3], v[16:17] op_sel_hi:[1,0]
	v_pk_mul_f32 v[2:3], v[0:1], v[16:17] op_sel_hi:[1,0]
	v_cvt_pk_bf16_f32 v0, v4, v5
	v_cvt_pk_bf16_f32 v1, v6, v7
	v_cvt_pk_bf16_f32 v2, v2, v3
	v_cvt_pk_bf16_f32 v3, v8, v9
	s_andn2_b64 vcc, exec, s[4:5]
	global_store_dwordx4 v[18:19], v[0:3], off offset:256
	s_cbranch_vccnz .LBB0_371
	s_and_b64 vcc, exec, s[2:3]
	v_mbcnt_lo_u32_b32 v0, -1, 0
	v_mbcnt_hi_u32_b32 v0, -1, v0
	s_cbranch_vccnz .LBB0_370
	s_barrier
	s_branch .LBB0_370

; __device__ __forceinline__ unsigned cvt_pk_bf16(float lo, float hi) { const f32x2 v = {lo, hi}; const bf16x2_t b = __builtin_convertvector(v, bf16x2_t); return __builtin_bit_cast(unsigned, b); }
; __global__ void __launch_bounds__(NWAVES * 64, 2) mk_fwd(Args args) {
;     ...
;         for (int it = gw; it < T * 4; it += NGW) {
;             const size_t off = (size_t)it * 256 + lane * 4; const int tok = it >> 2, fo = (tok >> 11) * 1024 + (it & 3) * 256 + lane * 4;
;             const f32x4 a0 = __builtin_nontemporal_load((const f32x4*)(XS + off)), a1 = __builtin_nontemporal_load((const f32x4*)(XS + (size_t)T * 1024 + off)), sx = *(const f32x4*)(SXV + fo), cx = *(const f32x4*)(CXV + fo);
;             const f32x2 st = *(const f32x2*)(RS1 + (size_t)tok * 2);
;             const float mean = st.x * (1.0f / D), rstd = rsqrtf(st.y * (1.0f / D) - mean * mean + LN_EPS);
;             const f32x4 a = (((a0 + a1) - sx * mean) * rstd + cx) * 0.03125f;
;             const float mx = wave_max(fmaxf(fmaxf(a[0], a[1]), fmaxf(a[2], a[3])));
;             f32x4 e; e[0] = __expf(a[0] - mx); e[1] = __expf(a[1] - mx); e[2] = __expf(a[2] - mx); e[3] = __expf(a[3] - mx);
;             const float inv = 1.0f / wave_sum((e[0] + e[1]) + (e[2] + e[3]));
;             u32x2 w; w.x = cvt_pk_bf16(e[0] * inv, e[1] * inv); w.y = cvt_pk_bf16(e[2] * inv, e[3] * inv);
;             *(u32x2*)(XP + off) = w;
.LBB0_1208:
	s_cmp_lt_i32 s86, 15
	s_cselect_b64 s[0:1], -1, 0
	s_and_b64 s[4:5], s[0:1], s[2:3]
	s_andn2_b64 vcc, exec, s[4:5]
	s_cbranch_vccnz .LBB0_1213
	s_cmpk_gt_i32 s90, 0x7fff
	v_mbcnt_lo_u32_b32 v0, -1, 0
	v_mbcnt_hi_u32_b32 v0, -1, v0
	s_cbranch_scc1 .LBB0_1213
	s_waitcnt lgkmcnt(0)
	v_mbcnt_lo_u32_b32 v2, -1, 0
	v_mbcnt_hi_u32_b32 v2, -1, v2
	v_and_b32_e32 v3, 64, v2
	v_add_u32_e32 v3, 64, v3
	v_xor_b32_e32 v4, 1, v2
	v_cmp_lt_i32_e32 vcc, v4, v3
	s_add_u32 s2, s78, 0x4d700000
	s_addc_u32 s3, s79, 0
	v_cndmask_b32_e32 v4, v2, v4, vcc
	v_lshlrev_b32_e32 v6, 2, v4
	v_xor_b32_e32 v4, 2, v2
	v_cmp_lt_i32_e32 vcc, v4, v3
	s_add_u32 s6, s78, 0x4d704000
	s_addc_u32 s7, s79, 0
	v_cndmask_b32_e32 v4, v2, v4, vcc
	v_lshlrev_b32_e32 v7, 2, v4
	v_xor_b32_e32 v4, 4, v2
	v_cmp_lt_i32_e32 vcc, v4, v3
	s_add_u32 s0, s78, 0x20000
	s_addc_u32 s1, s79, 0
	v_cndmask_b32_e32 v4, v2, v4, vcc
	v_lshlrev_b32_e32 v8, 2, v4
	v_xor_b32_e32 v4, 8, v2
	v_cmp_lt_i32_e32 vcc, v4, v3
	s_ashr_i32 s91, s90, 31
	s_lshl_b64 s[8:9], s[90:91], 10
	v_cndmask_b32_e32 v4, v2, v4, vcc
	v_lshlrev_b32_e32 v9, 2, v4
	v_xor_b32_e32 v4, 16, v2
	v_cmp_lt_i32_e32 vcc, v4, v3
	v_lshlrev_b32_e32 v0, 2, v0
	s_add_u32 s8, s78, s8
	v_cndmask_b32_e32 v4, v2, v4, vcc
	v_lshlrev_b32_e32 v10, 2, v4
	v_xor_b32_e32 v4, 32, v2
	v_cmp_lt_i32_e32 vcc, v4, v3
	v_ashrrev_i32_e32 v1, 31, v0
	s_addc_u32 s9, s79, s9
	v_cndmask_b32_e32 v2, v2, v4, vcc
	v_lshlrev_b32_e32 v11, 2, v2
	v_lshl_add_u64 v[2:3], v[0:1], 2, s[8:9]
	s_mov_b64 s[8:9], 0x48700000
	s_ashr_i32 s83, s82, 31
	v_lshl_add_u64 v[2:3], v[2:3], 0, s[8:9]
	s_lshl_b64 s[8:9], s[82:83], 10
	s_lshl_b64 s[10:11], s[90:91], 9
	s_add_u32 s10, s78, s10
	s_addc_u32 s11, s79, s11
	v_readlane_b32 s12, v237, 57
	v_lshl_add_u64 v[4:5], v[0:1], 1, s[10:11]
	s_mov_b64 s[10:11], 0x4c700000
	s_lshl_b32 s12, s12, 11
	s_lshl_b32 s13, s93, 8
	v_lshl_add_u64 v[4:5], v[4:5], 0, s[10:11]
	s_lshl_b64 s[10:11], s[82:83], 9
	s_add_i32 s13, s12, s13
	s_lshl_b32 s17, s85, 11
	v_mov_b32_e32 v1, 0
	s_mov_b32 s12, 0x39800000
	s_mov_b32 s18, 0x800000
	s_mov_b32 s16, 0x3d000000
	s_mov_b32 s19, s90
	v_add_co_u32_e32 v40, vcc, 0x2000000, v2
	s_nop 1
	v_addc_co_u32_e32 v41, vcc, 0, v3, vcc
	global_load_dwordx4 v[32:35], v[2:3], off nt
	global_load_dwordx4 v[36:39], v[40:41], off nt
	s_waitcnt vmcnt(0)
.LBB0_1211:
	s_waitcnt vmcnt(1)
	v_mov_b32_e32 v12, v32
	v_mov_b32_e32 v13, v33
	v_mov_b32_e32 v14, v34
	v_mov_b32_e32 v15, v35
	v_mov_b32_e32 v16, v36
	v_mov_b32_e32 v17, v37
	v_mov_b32_e32 v18, v38
	v_mov_b32_e32 v19, v39
	s_ashr_i32 s20, s19, 2
	s_ashr_i32 s21, s19, 3
	s_and_b32 s22, s13, 0x300
	s_and_b32 s23, s21, 0xfffffc00
	s_ashr_i32 s21, s20, 31
	s_or_b32 s22, s23, s22
	s_lshl_b64 s[20:21], s[20:21], 3
	s_add_u32 s20, s0, s20
	s_addc_u32 s21, s1, s21
	v_add_u32_e32 v20, s22, v0
	v_ashrrev_i32_e32 v21, 31, v20
	global_load_dwordx2 v[28:29], v1, s[20:21]
	v_lshlrev_b64 v[20:21], 2, v[20:21]
	v_lshl_add_u64 v[22:23], s[2:3], 0, v[20:21]
	v_lshl_add_u64 v[24:25], s[6:7], 0, v[20:21]
	global_load_dwordx4 v[20:23], v[22:23], off
	s_nop 0
	global_load_dwordx4 v[24:27], v[24:25], off
	s_add_i32 s13, s13, s17
	s_add_i32 s19, s19, s82
	v_lshl_add_u64 v[2:3], v[2:3], 0, s[8:9]
	v_add_co_u32_e32 v40, vcc, 0x2000000, v2
	s_cmp_lt_i32 s19, 0x8000
	s_nop 0
	v_addc_co_u32_e32 v41, vcc, 0, v3, vcc
	global_load_dwordx4 v[32:35], v[2:3], off nt
	global_load_dwordx4 v[36:39], v[40:41], off nt
	s_waitcnt vmcnt(2)
	v_pk_add_f32 v[12:13], v[12:13], v[16:17]
	v_pk_add_f32 v[14:15], v[14:15], v[18:19]
	v_pk_mul_f32 v[16:17], v[28:29], s[12:13] op_sel_hi:[1,0]
	v_xor_b32_e32 v19, 0x80000000, v23
	v_fma_f32 v18, -v16, v16, v17
	v_add_f32_e32 v28, 0x3727c5ac, v18
	v_xor_b32_e32 v18, 0x80000000, v22
	v_pk_fma_f32 v[12:13], v[20:21], v[16:17], v[12:13] op_sel_hi:[1,0,1] neg_lo:[1,0,0] neg_hi:[1,0,0]
	v_mul_f32_e32 v20, 0x4b800000, v28
	v_cmp_gt_f32_e32 vcc, s18, v28
	v_pk_fma_f32 v[14:15], v[18:19], v[16:17], v[14:15] op_sel_hi:[1,0,1]
	s_nop 0
	v_cndmask_b32_e32 v16, v28, v20, vcc
	v_rsq_f32_e32 v16, v16
	s_nop 0
	v_mul_f32_e32 v17, 0x45800000, v16
	v_cndmask_b32_e32 v16, v16, v17, vcc
	v_pk_fma_f32 v[14:15], v[14:15], v[16:17], v[26:27] op_sel_hi:[1,0,1]
	v_pk_fma_f32 v[12:13], v[12:13], v[16:17], v[24:25] op_sel_hi:[1,0,1]
	v_pk_mul_f32 v[14:15], v[14:15], s[16:17] op_sel_hi:[1,0]
	v_pk_mul_f32 v[12:13], v[12:13], s[16:17] op_sel_hi:[1,0]
	v_max_f32_e32 v16, v14, v15
	v_max3_f32 v16, v12, v13, v16
	ds_bpermute_b32 v17, v6, v16
	s_waitcnt lgkmcnt(0)
	v_max_f32_e32 v17, v17, v17
	v_max_f32_e32 v16, v16, v17
	ds_bpermute_b32 v17, v7, v16
	s_waitcnt lgkmcnt(0)
	v_max_f32_e32 v17, v17, v17
	v_max_f32_e32 v16, v16, v17
	ds_bpermute_b32 v17, v8, v16
	s_waitcnt lgkmcnt(0)
	v_max_f32_e32 v17, v17, v17
	v_max_f32_e32 v16, v16, v17
	ds_bpermute_b32 v17, v9, v16
	s_waitcnt lgkmcnt(0)
	v_max_f32_e32 v17, v17, v17
	v_max_f32_e32 v16, v16, v17
	ds_bpermute_b32 v17, v10, v16
	s_waitcnt lgkmcnt(0)
	v_max_f32_e32 v17, v17, v17
	v_max_f32_e32 v16, v16, v17
	ds_bpermute_b32 v17, v11, v16
	s_waitcnt lgkmcnt(0)
	v_max_f32_e32 v17, v17, v17
	v_max_f32_e32 v16, v16, v17
	v_sub_f32_e32 v12, v12, v16
	v_sub_f32_e32 v13, v13, v16
	v_sub_f32_e32 v14, v14, v16
	v_sub_f32_e32 v15, v15, v16
	v_mul_f32_e32 v12, 0x3fb8aa3b, v12
	v_mul_f32_e32 v13, 0x3fb8aa3b, v13
	v_mul_f32_e32 v16, 0x3fb8aa3b, v14
	v_mul_f32_e32 v15, 0x3fb8aa3b, v15
	v_exp_f32_e32 v12, v12
	v_exp_f32_e32 v14, v13
	v_exp_f32_e32 v13, v16
	v_exp_f32_e32 v15, v15
	v_mov_b32_e32 v18, v12
	v_mov_b32_e32 v19, v14
	v_pk_add_f32 v[16:17], v[12:13], v[14:15]
	s_nop 0
	v_add_f32_e32 v12, v16, v17
	v_mov_b32_e32 v14, v13
	ds_bpermute_b32 v13, v6, v12
	s_waitcnt lgkmcnt(0)
	v_add_f32_e32 v12, v12, v13
	ds_bpermute_b32 v13, v7, v12
	s_waitcnt lgkmcnt(0)
	v_add_f32_e32 v12, v12, v13
	ds_bpermute_b32 v13, v8, v12
	s_waitcnt lgkmcnt(0)
	v_add_f32_e32 v12, v12, v13
	ds_bpermute_b32 v13, v9, v12
	s_waitcnt lgkmcnt(0)
	v_add_f32_e32 v12, v12, v13
	ds_bpermute_b32 v13, v10, v12
	s_waitcnt lgkmcnt(0)
	v_add_f32_e32 v12, v12, v13
	ds_bpermute_b32 v13, v11, v12
	s_waitcnt lgkmcnt(0)
	v_add_f32_e32 v12, v12, v13
	v_div_scale_f32 v13, s[20:21], v12, v12, 1.0
	v_rcp_f32_e32 v17, v13
	v_div_scale_f32 v16, vcc, 1.0, v12, 1.0
	v_fma_f32 v20, -v13, v17, 1.0
	v_fmac_f32_e32 v17, v20, v17
	v_mul_f32_e32 v20, v16, v17
	v_fma_f32 v21, -v13, v20, v16
	v_fmac_f32_e32 v20, v21, v17
	v_fma_f32 v13, -v13, v20, v16
	v_div_fmas_f32 v13, v13, v17, v20
	v_div_fixup_f32 v12, v13, v12, 1.0
	v_pk_mul_f32 v[16:17], v[18:19], v[12:13] op_sel_hi:[1,0]
	v_pk_mul_f32 v[12:13], v[14:15], v[12:13] op_sel_hi:[1,0]
	v_cvt_pk_bf16_f32 v14, v16, v17
	v_cvt_pk_bf16_f32 v15, v12, v13
	global_store_dwordx2 v[4:5], v[14:15], off
	v_lshl_add_u64 v[4:5], v[4:5], 0, s[10:11]
	s_cbranch_scc1 .LBB0_1211
	v_readlane_b32 s14, v236, 14
